# UP main loop: second B half-tile of K-tile t+2 staged in the third segment instead of the second (pieces per segment 2/4/4/6 instead of 2/6/2/6), second-segment waits vmcnt 8->6 and relaxed 16->14; on
# speedup vs baseline: 1.0127x; 1.0073x over previous
.Lrx_skip_27:
	s_waitcnt vmcnt(16)
	s_waitcnt lgkmcnt(0)
	s_barrier
	s_setprio 1
	v_mfma_f32_16x16x32_bf16 v[122:125], v[140:143], v[214:217], v[122:125]
	v_mfma_f32_16x16x32_bf16 v[114:117], v[148:151], v[214:217], v[114:117]
	v_mfma_f32_16x16x32_bf16 v[106:109], v[140:143], v[222:225], v[106:109]
	v_mfma_f32_16x16x32_bf16 v[98:101], v[148:151], v[222:225], v[98:101]
	v_mfma_f32_16x16x32_bf16 v[90:93], v[140:143], v[230:233], v[90:93]
	v_mfma_f32_16x16x32_bf16 v[82:85], v[148:151], v[230:233], v[82:85]
	v_mfma_f32_16x16x32_bf16 v[74:77], v[140:143], v[238:241], v[74:77]
	v_mfma_f32_16x16x32_bf16 v[66:69], v[148:151], v[238:241], v[66:69]
	v_mfma_f32_16x16x32_bf16 v[122:125], v[144:147], v[218:221], v[122:125]
	v_mfma_f32_16x16x32_bf16 v[114:117], v[152:155], v[218:221], v[114:117]
	v_mfma_f32_16x16x32_bf16 v[106:109], v[144:147], v[226:229], v[106:109]
	v_mfma_f32_16x16x32_bf16 v[98:101], v[152:155], v[226:229], v[98:101]
	v_mfma_f32_16x16x32_bf16 v[90:93], v[144:147], v[234:237], v[90:93]
	v_mfma_f32_16x16x32_bf16 v[82:85], v[152:155], v[234:237], v[82:85]
	v_mfma_f32_16x16x32_bf16 v[74:77], v[144:147], v[242:245], v[74:77]
	v_mfma_f32_16x16x32_bf16 v[66:69], v[152:155], v[242:245], v[66:69]
	s_setprio 0
	s_setprio 1
	v_mfma_f32_16x16x32_bf16 v[126:129], v[182:185], v[214:217], v[126:129]
	v_mfma_f32_16x16x32_bf16 v[118:121], v[190:193], v[214:217], v[118:121]
	v_mfma_f32_16x16x32_bf16 v[110:113], v[182:185], v[222:225], v[110:113]
	v_mfma_f32_16x16x32_bf16 v[102:105], v[190:193], v[222:225], v[102:105]
	v_mfma_f32_16x16x32_bf16 v[94:97], v[182:185], v[230:233], v[94:97]
	v_mfma_f32_16x16x32_bf16 v[86:89], v[190:193], v[230:233], v[86:89]
	v_mfma_f32_16x16x32_bf16 v[78:81], v[182:185], v[238:241], v[78:81]
	v_mfma_f32_16x16x32_bf16 v[70:73], v[190:193], v[238:241], v[70:73]
	v_mfma_f32_16x16x32_bf16 v[126:129], v[186:189], v[218:221], v[126:129]
	v_mfma_f32_16x16x32_bf16 v[118:121], v[210:213], v[218:221], v[118:121]
	v_mfma_f32_16x16x32_bf16 v[110:113], v[186:189], v[226:229], v[110:113]
	v_mfma_f32_16x16x32_bf16 v[102:105], v[210:213], v[226:229], v[102:105]
	v_mfma_f32_16x16x32_bf16 v[94:97], v[186:189], v[234:237], v[94:97]
	v_mfma_f32_16x16x32_bf16 v[86:89], v[210:213], v[234:237], v[86:89]
	v_mfma_f32_16x16x32_bf16 v[78:81], v[186:189], v[242:245], v[78:81]
	v_mfma_f32_16x16x32_bf16 v[70:73], v[210:213], v[242:245], v[70:73]
	s_setprio 0
	s_barrier
	ds_read_b128 v[214:217], v139 offset:16384
	ds_read_b128 v[218:221], v139 offset:17408
	ds_read_b128 v[222:225], v139 offset:18432
	ds_read_b128 v[226:229], v139 offset:19456
	ds_read_b128 v[230:233], v139 offset:20480
	ds_read_b128 v[234:237], v139 offset:21504
	ds_read_b128 v[238:241], v139 offset:22528
	ds_read_b128 v[242:245], v139 offset:23552
	s_mov_b32 m0, s52
	s_nop 0
	global_load_lds_dwordx4 v132, s[44:45]
	s_mov_b32 m0, s53
	s_nop 0
	global_load_lds_dwordx4 v134, s[44:45]
	s_nop 0
	s_mov_b32 m0, s35
	s_nop 0
	global_load_lds_dwordx4 v0, s[48:49]
	s_nop 0
	s_mov_b32 m0, s56
	s_nop 0
	global_load_lds_dwordx4 v133, s[48:49]
	s_cmp_lg_u32 s18, 0
	s_cbranch_scc1 .Lrx_skip_28
	s_waitcnt vmcnt(6)
.Lrx_skip_28:
	s_waitcnt vmcnt(14)
	s_waitcnt lgkmcnt(0)
	s_barrier
	s_setprio 1
	v_mfma_f32_16x16x32_bf16 v[58:61], v[140:143], v[214:217], v[58:61]
	v_mfma_f32_16x16x32_bf16 v[50:53], v[148:151], v[214:217], v[50:53]
	v_mfma_f32_16x16x32_bf16 v[42:45], v[140:143], v[222:225], v[42:45]
	v_mfma_f32_16x16x32_bf16 v[34:37], v[148:151], v[222:225], v[34:37]
	v_mfma_f32_16x16x32_bf16 v[26:29], v[140:143], v[230:233], v[26:29]
	v_mfma_f32_16x16x32_bf16 v[18:21], v[148:151], v[230:233], v[18:21]
	v_mfma_f32_16x16x32_bf16 v[10:13], v[140:143], v[238:241], v[10:13]
	v_mfma_f32_16x16x32_bf16 v[2:5], v[148:151], v[238:241], v[2:5]
	v_mfma_f32_16x16x32_bf16 v[58:61], v[144:147], v[218:221], v[58:61]
	v_mfma_f32_16x16x32_bf16 v[50:53], v[152:155], v[218:221], v[50:53]
	v_mfma_f32_16x16x32_bf16 v[42:45], v[144:147], v[226:229], v[42:45]
	v_mfma_f32_16x16x32_bf16 v[34:37], v[152:155], v[226:229], v[34:37]
	v_mfma_f32_16x16x32_bf16 v[26:29], v[144:147], v[234:237], v[26:29]
	v_mfma_f32_16x16x32_bf16 v[18:21], v[152:155], v[234:237], v[18:21]
	v_mfma_f32_16x16x32_bf16 v[10:13], v[144:147], v[242:245], v[10:13]
	v_mfma_f32_16x16x32_bf16 v[2:5], v[152:155], v[242:245], v[2:5]
	s_setprio 0
	s_setprio 1
	v_mfma_f32_16x16x32_bf16 v[62:65], v[182:185], v[214:217], v[62:65]
	v_mfma_f32_16x16x32_bf16 v[54:57], v[190:193], v[214:217], v[54:57]
	v_mfma_f32_16x16x32_bf16 v[46:49], v[182:185], v[222:225], v[46:49]
	v_mfma_f32_16x16x32_bf16 v[38:41], v[190:193], v[222:225], v[38:41]
	v_mfma_f32_16x16x32_bf16 v[30:33], v[182:185], v[230:233], v[30:33]
	v_mfma_f32_16x16x32_bf16 v[22:25], v[190:193], v[230:233], v[22:25]
	v_mfma_f32_16x16x32_bf16 v[14:17], v[182:185], v[238:241], v[14:17]
	v_mfma_f32_16x16x32_bf16 v[6:9], v[190:193], v[238:241], v[6:9]
	v_mfma_f32_16x16x32_bf16 v[62:65], v[186:189], v[218:221], v[62:65]
	v_mfma_f32_16x16x32_bf16 v[54:57], v[210:213], v[218:221], v[54:57]
	v_mfma_f32_16x16x32_bf16 v[46:49], v[186:189], v[226:229], v[46:49]
	v_mfma_f32_16x16x32_bf16 v[38:41], v[210:213], v[226:229], v[38:41]
	v_mfma_f32_16x16x32_bf16 v[30:33], v[186:189], v[234:237], v[30:33]
	v_mfma_f32_16x16x32_bf16 v[22:25], v[210:213], v[234:237], v[22:25]
	v_mfma_f32_16x16x32_bf16 v[14:17], v[186:189], v[242:245], v[14:17]
	v_mfma_f32_16x16x32_bf16 v[6:9], v[210:213], v[242:245], v[6:9]
	s_setprio 0
	s_barrier
	v_add_u32_e32 v130, 0x18000, v138
	ds_read_b128 v[140:143], v130
	ds_read_b128 v[144:147], v130 offset:1024
	ds_read_b128 v[148:151], v130 offset:2048
	ds_read_b128 v[152:155], v130 offset:3072
	v_add_u32_e32 v130, 0x1c000, v138
	ds_read_b128 v[182:185], v130
	ds_read_b128 v[186:189], v130 offset:1024
	ds_read_b128 v[190:193], v130 offset:2048
	ds_read_b128 v[210:213], v130 offset:3072
	ds_read_b128 v[214:217], v139 offset:32768
	ds_read_b128 v[218:221], v139 offset:33792
	ds_read_b128 v[222:225], v139 offset:34816
	ds_read_b128 v[226:229], v139 offset:35840
	ds_read_b128 v[230:233], v139 offset:36864
	ds_read_b128 v[234:237], v139 offset:37888
	ds_read_b128 v[238:241], v139 offset:38912
	ds_read_b128 v[242:245], v139 offset:39936
	s_add_u32 s8, s44, 0x40000
	s_addc_u32 s9, s45, 0
	s_mov_b32 m0, s54
	s_nop 0
	global_load_lds_dwordx4 v132, s[8:9]
	s_nop 0
	s_mov_b32 m0, s55
	s_nop 0
	global_load_lds_dwordx4 v134, s[8:9]
	s_nop 0
	s_add_u32 s8, s48, 0x40000
	s_addc_u32 s9, s49, 0
	s_mov_b32 m0, s57
	s_nop 0
	global_load_lds_dwordx4 v0, s[8:9]
	s_nop 0
	s_mov_b32 m0, s58
	s_nop 0
	global_load_lds_dwordx4 v133, s[8:9]
	s_cmp_lg_u32 s18, 0
	s_cbranch_scc1 .Lrx_skip_29
	s_waitcnt vmcnt(8)
